# lnffn (layer 0): gate/shift/scale vectors loaded at the top of each row into AGPRs, overlapping the expert-row gather
# speedup vs baseline: 1.0136x; 1.0042x over previous
.LBB0_1049:
	s_waitcnt vmcnt(0)
	v_add_u32_e32 v5, 0xffffe000, v22
	v_lshrrev_b32_e32 v5, 11, v5
	v_add_u32_e32 v5, 1, v5
	s_and_b64 s[0:1], exec, vcc
	v_cndmask_b32_e64 v21, 0, v5, s[4:5]
	v_mov_b64_e32 v[48:49], s[20:21]
	s_or_b64 s[12:13], s[0:1], s[12:13]
	v_mad_u64_u32 v[50:51], s[0:1], v21, s27, v[48:49]
	v_lshl_add_u64 v[74:75], v[50:51], 0, s[14:15]
	v_mov_b32_e32 v5, v1
	v_lshl_add_u64 v[50:51], v[74:75], 0, v[0:1]
	v_lshl_add_u64 v[70:71], v[74:75], 0, v[4:5]
	v_mov_b32_e32 v7, v1
	v_mov_b32_e32 v9, v1
	v_accvgpr_read_b32 v50, a40
	v_accvgpr_read_b32 v51, a41
	v_accvgpr_read_b32 v52, a42
	v_accvgpr_read_b32 v53, a43
	s_nop 0
	v_accvgpr_read_b32 v70, a44
	v_accvgpr_read_b32 v71, a45
	v_accvgpr_read_b32 v72, a46
	v_accvgpr_read_b32 v73, a47
	v_lshl_add_u64 v[78:79], v[74:75], 0, v[6:7]
	v_lshl_add_u64 v[74:75], v[74:75], 0, v[8:9]
	v_accvgpr_read_b32 v78, a48
	v_accvgpr_read_b32 v79, a49
	v_accvgpr_read_b32 v80, a50
	v_accvgpr_read_b32 v81, a51
	v_lshlrev_b32_e32 v86, 16, v28
	v_accvgpr_read_b32 v82, a52
	v_accvgpr_read_b32 v83, a53
	v_accvgpr_read_b32 v84, a54
	v_accvgpr_read_b32 v85, a55
	v_lshlrev_b32_e32 v74, 16, v30
	v_and_b32_e32 v75, 0xffff0000, v30
	v_lshlrev_b32_e32 v30, 16, v31
	v_and_b32_e32 v31, 0xffff0000, v31
	v_and_b32_e32 v87, 0xffff0000, v28
	v_lshlrev_b32_e32 v28, 16, v29
	v_and_b32_e32 v29, 0xffff0000, v29
	v_lshlrev_b32_e32 v88, 16, v26
	v_and_b32_e32 v89, 0xffff0000, v26
	v_lshlrev_b32_e32 v26, 16, v27
	v_and_b32_e32 v27, 0xffff0000, v27
	v_lshlrev_b32_e32 v90, 16, v24
	v_and_b32_e32 v91, 0xffff0000, v24
	v_lshlrev_b32_e32 v24, 16, v25
	v_and_b32_e32 v25, 0xffff0000, v25
	v_add_u32_e32 v21, 5, v21
	s_waitcnt vmcnt(3)
	v_pk_mul_f32 v[46:47], v[46:47], v[52:53]
	v_pk_mul_f32 v[44:45], v[44:45], v[50:51]
	s_waitcnt vmcnt(2)
	v_pk_mul_f32 v[42:43], v[42:43], v[72:73]
	v_pk_mul_f32 v[40:41], v[40:41], v[70:71]
	s_waitcnt vmcnt(1)
	v_pk_mul_f32 v[50:51], v[38:39], v[80:81]
	v_pk_mul_f32 v[52:53], v[36:37], v[78:79]
	s_waitcnt vmcnt(0)
	v_pk_mul_f32 v[70:71], v[32:33], v[84:85]
	v_pk_mul_f32 v[72:73], v[34:35], v[82:83]
	v_pk_fma_f32 v[36:37], v[74:75], s[16:17], v[44:45] op_sel_hi:[1,0,1]
	v_pk_fma_f32 v[38:39], v[30:31], s[16:17], v[46:47] op_sel_hi:[1,0,1]
	v_pk_fma_f32 v[32:33], v[86:87], s[16:17], v[40:41] op_sel_hi:[1,0,1]
	v_pk_fma_f32 v[34:35], v[28:29], s[16:17], v[42:43] op_sel_hi:[1,0,1]
	v_pk_mov_b32 v[40:41], v[36:37], v[38:39] op_sel:[1,0]
	v_mov_b32_e32 v42, v36
	v_mov_b32_e32 v43, v39
	v_pk_mov_b32 v[44:45], v[32:33], v[34:35] op_sel:[1,0]
	v_mov_b32_e32 v46, v32
	v_mov_b32_e32 v47, v35
	v_pk_add_f32 v[40:41], v[40:41], v[42:43]
	v_pk_add_f32 v[42:43], v[44:45], v[46:47]
	v_pk_fma_f32 v[28:29], v[26:27], s[16:17], v[50:51] op_sel_hi:[1,0,1]
	v_pk_fma_f32 v[30:31], v[88:89], s[16:17], v[52:53] op_sel_hi:[1,0,1]
	v_pk_fma_f32 v[24:25], v[24:25], s[16:17], v[70:71] op_sel_hi:[1,0,1]
	v_pk_fma_f32 v[26:27], v[90:91], s[16:17], v[72:73] op_sel_hi:[1,0,1]
	v_add_f32_e32 v23, v40, v41
	v_pk_add_f32 v[40:41], v[42:43], v[42:43] op_sel:[0,1] op_sel_hi:[1,0]
	v_add_f32_e32 v50, v30, v31
	v_add_f32_e32 v52, v28, v29
	v_mov_b32_e32 v71, v26
	v_mov_b32_e32 v51, v24
	v_mov_b32_e32 v53, v25
	v_add_f32_e32 v70, 0, v23
	v_mov_b32_e32 v41, v27
	v_pk_add_f32 v[44:45], v[50:51], v[52:53]
	v_pk_add_f32 v[40:41], v[70:71], v[40:41]
	s_nop 1
	v_accvgpr_read_b32 v50, a8
	v_accvgpr_read_b32 v51, a9
	v_accvgpr_read_b32 v52, a10
	v_accvgpr_read_b32 v53, a11
	s_nop 1
	v_accvgpr_read_b32 v70, a12
	v_accvgpr_read_b32 v71, a13
	v_accvgpr_read_b32 v72, a14
	v_accvgpr_read_b32 v73, a15
	v_pk_add_f32 v[40:41], v[40:41], v[44:45]
	s_nop 0
	v_add_f32_e32 v23, v40, v41
	v_mov_b32_e32 v40, v23
	s_nop 1
	v_add_f32_dpp v40, v40, v40 quad_perm:[1,0,3,2] row_mask:0xf bank_mask:0xf
	s_nop 1
	v_add_f32_dpp v40, v40, v40 quad_perm:[2,3,0,1] row_mask:0xf bank_mask:0xf
	s_nop 1
	v_add_f32_dpp v40, v40, v40 row_half_mirror row_mask:0xf bank_mask:0xf
	s_nop 1
	v_add_f32_dpp v40, v40, v40 row_mirror row_mask:0xf bank_mask:0xf
	s_nop 0
	v_readlane_b32 s44, v40, 0
	v_readlane_b32 s45, v40, 16
	v_readlane_b32 s46, v40, 32
	v_readlane_b32 s47, v40, 48
	s_nop 1
	v_mov_b32_e32 v40, s44
	v_add_f32_e32 v40, s45, v40
	v_add_f32_e32 v40, s46, v40
	v_add_f32_e32 v40, s47, v40
	v_mov_b32_e32 v23, v40
	v_fmamk_f32 v37, v23, 0xba800000, v37
	v_fmac_f32_e32 v36, 0xba800000, v23
	v_fmamk_f32 v39, v23, 0xba800000, v39
	v_fmac_f32_e32 v38, 0xba800000, v23
	v_fmamk_f32 v33, v23, 0xba800000, v33
	v_fmac_f32_e32 v32, 0xba800000, v23
	v_fmamk_f32 v35, v23, 0xba800000, v35
	v_fmac_f32_e32 v34, 0xba800000, v23
	v_pk_mul_f32 v[40:41], v[38:39], v[38:39]
	v_pk_mul_f32 v[42:43], v[36:37], v[36:37]
	v_pk_mul_f32 v[44:45], v[34:35], v[34:35]
	v_pk_mul_f32 v[46:47], v[32:33], v[32:33]
	v_fmac_f32_e32 v30, 0xba800000, v23
	v_fmac_f32_e32 v28, 0xba800000, v23
	v_pk_mov_b32 v[78:79], v[42:43], v[40:41] op_sel:[1,0]
	v_mov_b32_e32 v43, v41
	v_pk_mov_b32 v[40:41], v[46:47], v[44:45] op_sel:[1,0]
	v_mov_b32_e32 v47, v45
	v_fmamk_f32 v31, v23, 0xba800000, v31
	v_fmamk_f32 v29, v23, 0xba800000, v29
	v_mul_f32_e32 v74, v30, v30
	v_mul_f32_e32 v76, v28, v28
	v_pk_add_f32 v[42:43], v[78:79], v[42:43]
	v_pk_add_f32 v[40:41], v[40:41], v[46:47]
	v_fmamk_f32 v25, v23, 0xba800000, v25
	v_fmac_f32_e32 v24, 0xba800000, v23
	v_fmamk_f32 v27, v23, 0xba800000, v27
	v_fmac_f32_e32 v26, 0xba800000, v23
	v_pk_fma_f32 v[44:45], v[30:31], v[30:31], v[74:75] op_sel_hi:[1,1,0]
	v_pk_fma_f32 v[74:75], v[28:29], v[28:29], v[76:77] op_sel_hi:[1,1,0]
	v_pk_add_f32 v[42:43], v[42:43], v[42:43] op_sel_hi:[0,1]
	v_pk_add_f32 v[40:41], v[40:41], v[40:41] op_sel_hi:[0,1]
	v_mul_f32_e32 v44, v26, v26
	v_mul_f32_e32 v74, v27, v27
	v_mul_f32_e32 v42, v24, v24
	v_mul_f32_e32 v40, v25, v25
	v_pk_add_f32 v[44:45], v[44:45], v[74:75]
	v_pk_add_f32 v[40:41], v[42:43], v[40:41]
	v_mad_u64_u32 v[74:75], s[0:1], v21, s27, v[48:49]
	v_pk_add_f32 v[40:41], v[44:45], v[40:41]
	v_lshl_add_u64 v[42:43], v[74:75], 0, s[18:19]
	v_add_f32_e32 v23, v40, v41
	v_mov_b32_e32 v40, v23
	s_nop 1
	v_add_f32_dpp v40, v40, v40 quad_perm:[1,0,3,2] row_mask:0xf bank_mask:0xf
	s_nop 1
	v_add_f32_dpp v40, v40, v40 quad_perm:[2,3,0,1] row_mask:0xf bank_mask:0xf
	s_nop 1
	v_add_f32_dpp v40, v40, v40 row_half_mirror row_mask:0xf bank_mask:0xf
	s_nop 1
	v_add_f32_dpp v40, v40, v40 row_mirror row_mask:0xf bank_mask:0xf
	s_nop 0
	v_readlane_b32 s44, v40, 0
	v_readlane_b32 s45, v40, 16
	v_readlane_b32 s46, v40, 32
	v_readlane_b32 s47, v40, 48
	s_nop 1
	v_mov_b32_e32 v40, s44
	v_add_f32_e32 v40, s45, v40
	v_add_f32_e32 v40, s46, v40
	v_add_f32_e32 v40, s47, v40
	v_lshl_add_u64 v[46:47], v[42:43], 0, v[0:1]
	v_ashrrev_i32_e32 v23, 31, v22
	v_lshlrev_b64 v[22:23], 11, v[22:23]
	v_mov_b32_e32 v21, v40
	v_fmamk_f32 v21, v21, 0x3a800000, v54
	v_mul_f32_e32 v40, 0x4b800000, v21
	v_cmp_gt_f32_e32 vcc, s28, v21
	s_nop 1
	v_cndmask_b32_e32 v21, v21, v40, vcc
	v_rsq_f32_e32 v21, v21
	v_lshl_add_u64 v[40:41], v[2:3], 0, v[22:23]
	v_lshl_add_u64 v[22:23], v[14:15], 0, v[22:23]
	v_mul_f32_e32 v44, 0x45800000, v21
	v_cndmask_b32_e32 v44, v21, v44, vcc
	v_pk_mul_f32 v[36:37], v[36:37], v[44:45] op_sel_hi:[1,0]
	v_pk_mul_f32 v[38:39], v[38:39], v[44:45] op_sel_hi:[1,0]
	v_pk_fma_f32 v[70:71], v[50:51], v[36:37], v[70:71]
	v_pk_fma_f32 v[38:39], v[52:53], v[38:39], v[72:73]
	v_cvt_pk_bf16_f32 v36, v70, v71
	v_pk_mul_f32 v[32:33], v[32:33], v[44:45] op_sel_hi:[1,0]
	v_cvt_pk_bf16_f32 v37, v38, v39
	global_store_dwordx2 v[40:41], v[36:37], off
	s_nop 1
	v_accvgpr_read_b32 v46, a56
	v_accvgpr_read_b32 v47, a57
	v_accvgpr_read_b32 v48, a58
	v_accvgpr_read_b32 v49, a59
	v_lshl_add_u64 v[36:37], v[74:75], 0, v[0:1]
	v_accvgpr_read_b32 v50, a72
	v_accvgpr_read_b32 v51, a73
	v_accvgpr_read_b32 v52, a74
	v_accvgpr_read_b32 v53, a75
	v_pk_mul_f32 v[34:35], v[34:35], v[44:45] op_sel_hi:[1,0]
	v_pk_mul_f32 v[30:31], v[30:31], v[44:45] op_sel_hi:[1,0]
	v_pk_mul_f32 v[28:29], v[28:29], v[44:45] op_sel_hi:[1,0]
	v_pk_mul_f32 v[26:27], v[26:27], v[44:45] op_sel_hi:[1,0]
	v_pk_mul_f32 v[24:25], v[24:25], v[44:45] op_sel_hi:[1,0]
	v_pk_add_f32 v[46:47], v[46:47], 1.0 op_sel_hi:[1,0]
	v_pk_add_f32 v[48:49], v[48:49], 1.0 op_sel_hi:[1,0]
	v_pk_fma_f32 v[46:47], v[46:47], v[70:71], v[50:51]
	v_pk_fma_f32 v[38:39], v[48:49], v[38:39], v[52:53]
	v_cvt_pk_bf16_f32 v46, v46, v47
	s_nop 0
	v_cvt_pk_bf16_f32 v47, v38, v39
	global_store_dwordx2 v[22:23], v[46:47], off
	s_nop 1
	v_accvgpr_read_b32 v46, a16
	v_accvgpr_read_b32 v47, a17
	v_accvgpr_read_b32 v48, a18
	v_accvgpr_read_b32 v49, a19
	s_nop 0
	s_nop 1
	v_accvgpr_read_b32 v50, a20
	v_accvgpr_read_b32 v51, a21
	v_accvgpr_read_b32 v52, a22
	v_accvgpr_read_b32 v53, a23
	v_lshl_add_u64 v[38:39], v[42:43], 0, v[4:5]
	v_mov_b32_e32 v5, v61
	v_pk_fma_f32 v[52:53], v[48:49], v[34:35], v[52:53]
	v_pk_fma_f32 v[50:51], v[46:47], v[32:33], v[50:51]
	s_nop 0
	v_cvt_pk_bf16_f32 v32, v50, v51
	v_cvt_pk_bf16_f32 v33, v52, v53
	global_store_dwordx2 v[40:41], v[32:33], off offset:512
	s_nop 1
	v_accvgpr_read_b32 v32, a60
	v_accvgpr_read_b32 v33, a61
	v_accvgpr_read_b32 v34, a62
	v_accvgpr_read_b32 v35, a63
	s_nop 0
	v_accvgpr_read_b32 v46, a76
	v_accvgpr_read_b32 v47, a77
	v_accvgpr_read_b32 v48, a78
	v_accvgpr_read_b32 v49, a79
	v_lshl_add_u64 v[38:39], v[42:43], 0, v[6:7]
	v_pk_add_f32 v[32:33], v[32:33], 1.0 op_sel_hi:[1,0]
	v_pk_add_f32 v[34:35], v[34:35], 1.0 op_sel_hi:[1,0]
	v_pk_fma_f32 v[32:33], v[32:33], v[50:51], v[46:47]
	v_pk_fma_f32 v[34:35], v[34:35], v[52:53], v[48:49]
	v_cvt_pk_bf16_f32 v32, v32, v33
	s_nop 0
	v_cvt_pk_bf16_f32 v33, v34, v35
	global_store_dwordx2 v[22:23], v[32:33], off offset:512
	s_nop 1
	v_accvgpr_read_b32 v32, a24
	v_accvgpr_read_b32 v33, a25
	v_accvgpr_read_b32 v34, a26
	v_accvgpr_read_b32 v35, a27
	s_nop 0
	s_nop 1
	v_accvgpr_read_b32 v46, a28
	v_accvgpr_read_b32 v47, a29
	v_accvgpr_read_b32 v48, a30
	v_accvgpr_read_b32 v49, a31
	v_pk_fma_f32 v[48:49], v[34:35], v[28:29], v[48:49]
	v_pk_fma_f32 v[46:47], v[32:33], v[30:31], v[46:47]
	s_nop 0
	v_cvt_pk_bf16_f32 v28, v46, v47
	v_cvt_pk_bf16_f32 v29, v48, v49
	global_store_dwordx2 v[40:41], v[28:29], off offset:1024
	s_nop 1
	v_accvgpr_read_b32 v28, a64
	v_accvgpr_read_b32 v29, a65
	v_accvgpr_read_b32 v30, a66
	v_accvgpr_read_b32 v31, a67
	s_nop 0
	v_accvgpr_read_b32 v32, a80
	v_accvgpr_read_b32 v33, a81
	v_accvgpr_read_b32 v34, a82
	v_accvgpr_read_b32 v35, a83
	v_lshl_add_u64 v[38:39], v[42:43], 0, v[8:9]
	v_pk_add_f32 v[28:29], v[28:29], 1.0 op_sel_hi:[1,0]
	v_pk_add_f32 v[30:31], v[30:31], 1.0 op_sel_hi:[1,0]
	v_pk_fma_f32 v[28:29], v[28:29], v[46:47], v[32:33]
	v_pk_fma_f32 v[30:31], v[30:31], v[48:49], v[34:35]
	v_cvt_pk_bf16_f32 v28, v28, v29
	s_nop 0
	v_cvt_pk_bf16_f32 v29, v30, v31
	global_store_dwordx2 v[22:23], v[28:29], off offset:1024
	s_nop 1
	v_accvgpr_read_b32 v28, a32
	v_accvgpr_read_b32 v29, a33
	v_accvgpr_read_b32 v30, a34
	v_accvgpr_read_b32 v31, a35
	s_nop 0
	s_nop 1
	v_accvgpr_read_b32 v32, a36
	v_accvgpr_read_b32 v33, a37
	v_accvgpr_read_b32 v34, a38
	v_accvgpr_read_b32 v35, a39
	v_pk_fma_f32 v[42:43], v[24:25], v[30:31], v[34:35]
	v_pk_fma_f32 v[44:45], v[26:27], v[28:29], v[32:33]
	v_mov_b64_e32 v[30:31], v[62:63]
	v_cvt_pk_bf16_f32 v24, v44, v45
	v_cvt_pk_bf16_f32 v25, v42, v43
	global_store_dwordx2 v[40:41], v[24:25], off offset:1536
	s_nop 1
	v_accvgpr_read_b32 v32, a68
	v_accvgpr_read_b32 v33, a69
	v_accvgpr_read_b32 v34, a70
	v_accvgpr_read_b32 v35, a71
	s_nop 0
	v_accvgpr_read_b32 v36, a84
	v_accvgpr_read_b32 v37, a85
	v_accvgpr_read_b32 v38, a86
	v_accvgpr_read_b32 v39, a87
	v_mov_b64_e32 v[28:29], v[64:65]
	v_mov_b64_e32 v[26:27], v[66:67]
	v_mov_b64_e32 v[24:25], v[68:69]
	v_pk_add_f32 v[32:33], v[32:33], 1.0 op_sel_hi:[1,0]
	v_pk_add_f32 v[34:35], v[34:35], 1.0 op_sel_hi:[1,0]
	v_pk_fma_f32 v[32:33], v[44:45], v[32:33], v[36:37]
	v_pk_fma_f32 v[34:35], v[42:43], v[34:35], v[38:39]
	v_cvt_pk_bf16_f32 v32, v32, v33
	s_nop 0
	v_cvt_pk_bf16_f32 v33, v34, v35
	global_store_dwordx2 v[22:23], v[32:33], off offset:1536
	v_mov_b32_e32 v22, v20
	s_andn2_b64 exec, exec, s[12:13]
	s_cbranch_execz .LBB0_1055
.LBB0_1050:
	v_readfirstlane_b32 s58, v22
	s_sub_i32 s59, s58, 0x2000
	s_ashr_i32 s59, s59, 11
	s_add_i32 s59, s59, 1
	s_cmp_lt_i32 s58, 0x2000
	s_cselect_b32 s59, 0, s59
	s_mul_i32 s59, s59, 0x6000
	s_add_u32 s60, s20, s59
	s_addc_u32 s61, s21, 0
	s_add_u32 s62, s60, 0x1e000
	s_addc_u32 s63, s61, 0
	s_add_u32 s58, s60, 0x1f000
	s_addc_u32 s59, s61, 0
	s_add_u32 s60, s60, 0x5000
	s_addc_u32 s61, s61, 0
	global_load_dwordx4 a[40:43], v0, s[60:61]
	global_load_dwordx4 a[44:47], v0, s[60:61] offset:1024
	global_load_dwordx4 a[48:51], v0, s[60:61] offset:2048
	global_load_dwordx4 a[52:55], v0, s[60:61] offset:3072
	global_load_dwordx4 a[56:59], v0, s[58:59]
	global_load_dwordx4 a[72:75], v0, s[62:63]
	global_load_dwordx4 a[60:63], v0, s[58:59] offset:1024
	global_load_dwordx4 a[76:79], v0, s[62:63] offset:1024
	global_load_dwordx4 a[64:67], v0, s[58:59] offset:2048
	global_load_dwordx4 a[80:83], v0, s[62:63] offset:2048
	global_load_dwordx4 a[68:71], v0, s[58:59] offset:3072
	global_load_dwordx4 a[84:87], v0, s[62:63] offset:3072
	v_add_u32_e32 v20, s24, v22
	v_cmp_gt_i32_e64 s[4:5], s17, v20
	v_cmp_lt_i32_e32 vcc, s25, v20
	s_and_saveexec_b64 s[0:1], s[4:5]
	s_cbranch_execz .LBB0_1052
	v_ashrrev_i32_e32 v21, 31, v20
	v_lshlrev_b64 v[32:33], 6, v[20:21]
	v_lshl_add_u64 v[32:33], v[10:11], 0, v[32:33]
	v_lshlrev_b64 v[34:35], 11, v[20:21]
	v_lshl_add_u64 v[34:35], v[2:3], 0, v[34:35]
	global_load_dword v61, v[32:33], off
	global_load_dwordx2 v[62:63], v[34:35], off
	global_load_dwordx2 v[64:65], v[34:35], off offset:512
	global_load_dwordx2 v[66:67], v[34:35], off offset:1024
	global_load_dwordx2 v[68:69], v[34:35], off offset:1536

.LBB0_1209:
	s_or_b64 exec, exec, s[0:1]
	s_and_b32 s30, s21, 0x380
	v_ashrrev_i32_e32 v6, 4, v26
	v_add_u32_e32 v4, 0x200, v26
	v_and_b32_e32 v38, 15, v26
	v_add_u32_e32 v2, s30, v6
	v_ashrrev_i32_e32 v7, 4, v4
	v_lshlrev_b32_e32 v24, 4, v38
	v_ashrrev_i32_e32 v3, 31, v2
	v_add_u32_e32 v4, s30, v7
	v_lshl_add_u64 v[0:1], s[8:9], 0, v[24:25]
	v_lshlrev_b64 v[2:3], 8, v[2:3]
	v_ashrrev_i32_e32 v5, 31, v4
	v_lshl_add_u64 v[2:3], v[0:1], 0, v[2:3]
	v_lshlrev_b64 v[4:5], 8, v[4:5]
	v_lshl_add_u64 v[4:5], v[0:1], 0, v[4:5]
	s_mov_b64 exec, s[64:65]
	global_load_dwordx4 v[16:19], v[2:3], off
	global_load_dwordx4 v[28:31], v[4:5], off
	s_mov_b64 exec, -1
	v_add_u32_e32 v2, 0x400, v26
	v_ashrrev_i32_e32 v8, 4, v2
	v_add_u32_e32 v4, 0x600, v26
	v_add_u32_e32 v2, s30, v8
	v_ashrrev_i32_e32 v9, 4, v4
	v_ashrrev_i32_e32 v3, 31, v2
	v_add_u32_e32 v4, s30, v9
	v_lshlrev_b64 v[2:3], 8, v[2:3]
	v_ashrrev_i32_e32 v5, 31, v4
	v_lshl_add_u64 v[2:3], v[0:1], 0, v[2:3]
	v_lshlrev_b64 v[4:5], 8, v[4:5]
	v_lshl_add_u64 v[0:1], v[0:1], 0, v[4:5]
	s_mov_b64 exec, s[64:65]
	global_load_dwordx4 v[32:35], v[2:3], off
	global_load_dwordx4 v[40:43], v[0:1], off
	s_mov_b64 exec, -1
	v_and_b32_e32 v39, 0x7f, v26
	v_or_b32_e32 v0, s29, v39
	v_ashrrev_i32_e32 v1, 31, v0
	v_lshlrev_b64 v[0:1], 11, v[0:1]
	s_lshl_b32 s14, s30, 1
	v_and_b32_e32 v14, -8, v6
	s_lshl_b32 s31, s30, 2
	v_lshl_add_u64 v[0:1], s[10:11], 0, v[0:1]
	v_add_u32_e32 v2, 0, v24
	v_ashrrev_i32_e32 v15, 31, v14
	s_add_u32 s0, s66, s31
	v_lshl_add_u64 v[0:1], v[0:1], 0, s[14:15]
	v_mad_u64_u32 v[36:37], s[16:17], v6, s27, v[2:3]
	v_mad_u64_u32 v[48:49], s[16:17], v7, s27, v[2:3]
	v_mad_u64_u32 v[50:51], s[16:17], v8, s27, v[2:3]
	v_mad_u64_u32 v[52:53], s[16:17], v9, s27, v[2:3]
	v_lshl_add_u64 v[2:3], v[14:15], 1, v[0:1]
	s_addc_u32 s1, s67, 0
	v_and_b32_e32 v12, -8, v7
	v_and_b32_e32 v20, -8, v8
	v_and_b32_e32 v22, -8, v9
	global_load_dwordx4 v[44:47], v[2:3], off
	s_add_u32 s16, s68, s31
	v_ashrrev_i32_e32 v13, 31, v12
	v_ashrrev_i32_e32 v21, 31, v20
	v_ashrrev_i32_e32 v23, 31, v22
	v_lshlrev_b64 v[2:3], 2, v[14:15]
	s_addc_u32 s17, s69, 0
	v_lshl_add_u64 v[4:5], v[12:13], 1, v[0:1]
	v_lshl_add_u64 v[6:7], v[20:21], 1, v[0:1]
	v_lshl_add_u64 v[0:1], v[22:23], 1, v[0:1]
	v_lshl_add_u64 v[56:57], s[16:17], 0, v[2:3]
	v_lshl_add_u64 v[54:55], s[0:1], 0, v[2:3]
	global_load_dwordx4 v[8:11], v[4:5], off
	s_nop 0
	global_load_dwordx4 v[4:7], v[6:7], off
	s_nop 0
	global_load_dwordx4 v[0:3], v[0:1], off
	v_lshl_add_u32 v15, v39, 2, 0
	v_add_u32_e32 v27, 0x11000, v15
	s_waitcnt vmcnt(7)
	s_mov_b64 exec, s[64:65]
	ds_write_b128 v36, v[16:19]
	s_waitcnt vmcnt(6)
	ds_write_b128 v48, v[28:31]
	s_waitcnt vmcnt(5)
	ds_write_b128 v50, v[32:35]
	s_waitcnt vmcnt(4)
	ds_write_b128 v52, v[40:43]
	s_mov_b64 exec, -1
	s_waitcnt lgkmcnt(0)
	s_barrier
	s_mov_b64 exec, s[64:65]
	global_load_dwordx4 a[52:55], v[56:57], off
	global_load_dwordx4 a[56:59], v[54:55], off
	global_load_dwordx4 a[60:63], v[54:55], off offset:16
	global_load_dwordx4 a[64:67], v[56:57], off offset:16
	s_mov_b64 exec, -1
	v_add_u32_e32 v28, 0x11200, v15
	v_lshlrev_b64 v[48:49], 2, v[12:13]
	ds_read_b32 v13, v27
	ds_read_b32 v15, v28
	v_lshl_add_u64 v[50:51], s[0:1], 0, v[48:49]
	v_lshl_add_u64 v[48:49], s[16:17], 0, v[48:49]
	s_waitcnt vmcnt(7)
	v_lshlrev_b32_e32 v24, 16, v44
	v_and_b32_e32 v29, 0xffff0000, v44
	v_lshlrev_b32_e32 v44, 16, v45
	v_and_b32_e32 v45, 0xffff0000, v45
	v_lshlrev_b32_e32 v52, 16, v46
	v_and_b32_e32 v46, 0xffff0000, v46
	v_lshlrev_b32_e32 v53, 16, v47
	v_and_b32_e32 v47, 0xffff0000, v47
	s_waitcnt lgkmcnt(1)
	v_sub_f32_e32 v24, v24, v13
	v_sub_f32_e32 v29, v29, v13
	v_sub_f32_e32 v44, v44, v13
	v_sub_f32_e32 v45, v45, v13
	v_sub_f32_e32 v52, v52, v13
	v_sub_f32_e32 v46, v46, v13
	v_sub_f32_e32 v53, v53, v13
	v_sub_f32_e32 v13, v47, v13
	s_waitcnt lgkmcnt(0)
	v_mul_f32_e32 v24, v24, v15
	v_mul_f32_e32 v29, v29, v15
	v_mul_f32_e32 v44, v44, v15
	v_mul_f32_e32 v45, v45, v15
	v_mul_f32_e32 v47, v52, v15
	v_mul_f32_e32 v52, v53, v15
	v_mul_f32_e32 v13, v13, v15
	v_mul_f32_e32 v46, v46, v15
	s_waitcnt vmcnt(2)
	v_accvgpr_read_b32 v16, a52
	v_accvgpr_read_b32 v17, a53
	v_accvgpr_read_b32 v18, a54
	v_accvgpr_read_b32 v19, a55
	v_accvgpr_read_b32 v30, a56
	v_accvgpr_read_b32 v31, a57
	v_accvgpr_read_b32 v32, a58
	v_accvgpr_read_b32 v33, a59
	v_fma_f32 v15, v30, v24, v16
	v_fma_f32 v16, v31, v29, v17
	v_fma_f32 v17, v32, v44, v18
	v_fmac_f32_e32 v19, v33, v45
	s_waitcnt vmcnt(0)
	v_accvgpr_read_b32 v34, a60
	v_accvgpr_read_b32 v35, a61
	v_accvgpr_read_b32 v36, a62
	v_accvgpr_read_b32 v37, a63
	v_accvgpr_read_b32 v40, a64
	v_accvgpr_read_b32 v41, a65
	v_accvgpr_read_b32 v42, a66
	v_accvgpr_read_b32 v43, a67
	v_fma_f32 v18, v34, v47, v40
	v_fma_f32 v29, v36, v52, v42
	v_fmac_f32_e32 v43, v37, v13
	v_fma_f32 v24, v35, v46, v41
	v_cvt_pk_bf16_f32 v13, v15, v16
	v_cvt_pk_bf16_f32 v52, v17, v19
	v_cvt_pk_bf16_f32 v53, v18, v24
	v_cvt_pk_bf16_f32 v29, v29, v43
	s_mov_b64 exec, s[64:65]
	global_load_dwordx4 a[68:71], v[48:49], off
	global_load_dwordx4 a[72:75], v[50:51], off
	global_load_dwordx4 a[76:79], v[50:51], off offset:16
	global_load_dwordx4 a[80:83], v[48:49], off offset:16
	s_mov_b64 exec, -1
	ds_read_b32 v49, v27
	ds_read_b32 v50, v28
	v_lshl_add_u32 v24, v39, 1, 0
	v_mad_u64_u32 v[14:15], s[34:35], v14, s27, v[24:25]
	v_lshlrev_b64 v[44:45], 2, v[20:21]
	v_lshlrev_b32_e32 v15, 16, v8
	v_and_b32_e32 v8, 0xffff0000, v8
	v_lshlrev_b32_e32 v21, 16, v9
	v_and_b32_e32 v9, 0xffff0000, v9
	v_lshlrev_b32_e32 v39, 16, v10
	v_and_b32_e32 v10, 0xffff0000, v10
	v_lshlrev_b32_e32 v48, 16, v11
	v_and_b32_e32 v11, 0xffff0000, v11
	ds_write_b16 v14, v13 offset:34816
	ds_write_b16_d16_hi v14, v13 offset:35088
	ds_write_b16 v14, v52 offset:35360
	ds_write_b16_d16_hi v14, v52 offset:35632
	ds_write_b16 v14, v53 offset:35904
	ds_write_b16_d16_hi v14, v53 offset:36176
	ds_write_b16 v14, v29 offset:36448
	ds_write_b16_d16_hi v14, v29 offset:36720
	s_waitcnt lgkmcnt(9)
	v_sub_f32_e32 v13, v15, v49
	v_sub_f32_e32 v8, v8, v49
	v_sub_f32_e32 v14, v21, v49
	v_sub_f32_e32 v9, v9, v49
	v_sub_f32_e32 v15, v39, v49
	v_sub_f32_e32 v10, v10, v49
	v_sub_f32_e32 v21, v48, v49
	v_sub_f32_e32 v11, v11, v49
	s_waitcnt lgkmcnt(8)
	v_mul_f32_e32 v8, v8, v50
	v_mul_f32_e32 v14, v14, v50
	v_mul_f32_e32 v9, v9, v50
	v_mul_f32_e32 v15, v15, v50
	v_mul_f32_e32 v10, v10, v50
	v_mul_f32_e32 v21, v21, v50
	v_lshl_add_u64 v[46:47], s[0:1], 0, v[44:45]
	v_lshl_add_u64 v[44:45], s[16:17], 0, v[44:45]
	v_mul_f32_e32 v13, v13, v50
	v_mul_f32_e32 v11, v11, v50
	s_waitcnt vmcnt(2)
	v_accvgpr_read_b32 v16, a68
	v_accvgpr_read_b32 v17, a69
	v_accvgpr_read_b32 v18, a70
	v_accvgpr_read_b32 v19, a71
	v_accvgpr_read_b32 v30, a72
	v_accvgpr_read_b32 v31, a73
	v_accvgpr_read_b32 v32, a74
	v_accvgpr_read_b32 v33, a75
	v_fma_f32 v8, v31, v8, v17
	v_fma_f32 v14, v32, v14, v18
	v_fmac_f32_e32 v19, v33, v9
	s_waitcnt vmcnt(0)
	v_accvgpr_read_b32 v34, a76
	v_accvgpr_read_b32 v35, a77
	v_accvgpr_read_b32 v36, a78
	v_accvgpr_read_b32 v37, a79
	v_accvgpr_read_b32 v40, a80
	v_accvgpr_read_b32 v41, a81
	v_accvgpr_read_b32 v42, a82
	v_accvgpr_read_b32 v43, a83
	v_fma_f32 v9, v34, v15, v40
	v_fma_f32 v10, v35, v10, v41
	v_fma_f32 v15, v36, v21, v42
	v_fma_f32 v13, v30, v13, v16
	v_fmac_f32_e32 v43, v37, v11
	v_cvt_pk_bf16_f32 v21, v13, v8
	v_cvt_pk_bf16_f32 v29, v14, v19
	v_cvt_pk_bf16_f32 v39, v9, v10
	v_cvt_pk_bf16_f32 v48, v15, v43
	s_mov_b64 exec, s[64:65]
	global_load_dwordx4 a[84:87], v[44:45], off
	global_load_dwordx4 a[88:91], v[46:47], off
	global_load_dwordx4 a[92:95], v[46:47], off offset:16
	global_load_dwordx4 a[96:99], v[44:45], off offset:16
	s_mov_b64 exec, -1
	ds_read_b32 v44, v27
	ds_read_b32 v45, v28
	v_mad_u64_u32 v[12:13], s[34:35], v12, s27, v[24:25]
	v_lshlrev_b64 v[18:19], 2, v[22:23]
	v_lshl_add_u64 v[40:41], s[0:1], 0, v[18:19]
	v_lshl_add_u64 v[42:43], s[16:17], 0, v[18:19]
	v_lshlrev_b32_e32 v13, 16, v4
	v_and_b32_e32 v4, 0xffff0000, v4
	v_lshlrev_b32_e32 v18, 16, v5
	v_and_b32_e32 v5, 0xffff0000, v5
	v_lshlrev_b32_e32 v19, 16, v6
	v_and_b32_e32 v6, 0xffff0000, v6
	v_lshlrev_b32_e32 v23, 16, v7
	v_and_b32_e32 v7, 0xffff0000, v7
	ds_write_b16 v12, v21 offset:34816
	ds_write_b16_d16_hi v12, v21 offset:35088
	ds_write_b16 v12, v29 offset:35360
	ds_write_b16_d16_hi v12, v29 offset:35632
	ds_write_b16 v12, v39 offset:35904
	ds_write_b16_d16_hi v12, v39 offset:36176
	ds_write_b16 v12, v48 offset:36448
	ds_write_b16_d16_hi v12, v48 offset:36720
	s_waitcnt lgkmcnt(9)
	v_sub_f32_e32 v12, v13, v44
	v_sub_f32_e32 v4, v4, v44
	v_sub_f32_e32 v13, v18, v44
	v_sub_f32_e32 v5, v5, v44
	v_sub_f32_e32 v18, v19, v44
	v_sub_f32_e32 v6, v6, v44
	v_sub_f32_e32 v19, v23, v44
	v_sub_f32_e32 v7, v7, v44
	s_waitcnt lgkmcnt(8)
	v_mul_f32_e32 v12, v12, v45
	v_mul_f32_e32 v4, v4, v45
	v_mul_f32_e32 v13, v13, v45
	v_mul_f32_e32 v5, v5, v45
	v_mul_f32_e32 v18, v18, v45
	v_mul_f32_e32 v6, v6, v45
	v_mul_f32_e32 v19, v19, v45
	v_mul_f32_e32 v7, v7, v45
	v_bfe_u32 v39, v26, 4, 2
	v_ashrrev_i32_e32 v21, 2, v26
	v_and_b32_e32 v23, 0x4f, v26
	v_and_b32_e32 v66, 0xffffffe0, v21
	v_mad_u64_u32 v[20:21], s[0:1], v20, s27, v[24:25]
	v_lshlrev_b32_e32 v21, 16, v0
	v_and_b32_e32 v0, 0xffff0000, v0
	s_waitcnt vmcnt(2)
	v_accvgpr_read_b32 v8, a84
	v_accvgpr_read_b32 v9, a85
	v_accvgpr_read_b32 v10, a86
	v_accvgpr_read_b32 v11, a87
	v_accvgpr_read_b32 v14, a88
	v_accvgpr_read_b32 v15, a89
	v_accvgpr_read_b32 v16, a90
	v_accvgpr_read_b32 v17, a91
	v_fma_f32 v8, v14, v12, v8
	v_fma_f32 v4, v15, v4, v9
	v_fma_f32 v9, v16, v13, v10
	v_fmac_f32_e32 v11, v17, v5
	s_waitcnt vmcnt(0)
	v_accvgpr_read_b32 v30, a92
	v_accvgpr_read_b32 v31, a93
	v_accvgpr_read_b32 v32, a94
	v_accvgpr_read_b32 v33, a95
	v_accvgpr_read_b32 v34, a96
	v_accvgpr_read_b32 v35, a97
	v_accvgpr_read_b32 v36, a98
	v_accvgpr_read_b32 v37, a99
	v_fma_f32 v5, v30, v18, v34
	v_fma_f32 v6, v31, v6, v35
	v_fma_f32 v10, v32, v19, v36
	v_fmac_f32_e32 v37, v33, v7
	v_cvt_pk_bf16_f32 v29, v8, v4
	v_cvt_pk_bf16_f32 v31, v9, v11
	v_cvt_pk_bf16_f32 v32, v5, v6
	v_cvt_pk_bf16_f32 v33, v10, v37
	s_mov_b64 exec, s[64:65]
	global_load_dwordx4 a[100:103], v[42:43], off
	global_load_dwordx4 a[104:107], v[40:41], off
	global_load_dwordx4 a[108:111], v[40:41], off offset:16
	global_load_dwordx4 a[112:115], v[42:43], off offset:16
	s_mov_b64 exec, -1
	ds_read_b32 v27, v27
	ds_read_b32 v28, v28
	v_lshl_add_u32 v30, v39, 4, 0
	v_mad_u32_u24 v64, v23, s27, v30
	v_mad_u64_u32 v[22:23], s[0:1], v22, s27, v[24:25]
	v_lshlrev_b32_e32 v23, 16, v1
	v_and_b32_e32 v1, 0xffff0000, v1
	v_lshlrev_b32_e32 v24, 16, v2
	v_and_b32_e32 v2, 0xffff0000, v2
	v_lshlrev_b32_e32 v34, 16, v3
	v_and_b32_e32 v3, 0xffff0000, v3
	ds_write_b16 v20, v29 offset:34816
	ds_write_b16_d16_hi v20, v29 offset:35088
	ds_write_b16 v20, v31 offset:35360
	ds_write_b16_d16_hi v20, v31 offset:35632
	ds_write_b16 v20, v32 offset:35904
	ds_write_b16_d16_hi v20, v32 offset:36176
	ds_write_b16 v20, v33 offset:36448
	ds_write_b16_d16_hi v20, v33 offset:36720
	s_waitcnt lgkmcnt(9)
	v_sub_f32_e32 v20, v21, v27
	v_sub_f32_e32 v0, v0, v27
	v_sub_f32_e32 v21, v23, v27
	v_sub_f32_e32 v1, v1, v27
	v_sub_f32_e32 v23, v24, v27
	v_sub_f32_e32 v2, v2, v27
	v_sub_f32_e32 v24, v34, v27
	v_sub_f32_e32 v3, v3, v27
	s_waitcnt lgkmcnt(8)
	v_mul_f32_e32 v0, v0, v28
	v_mul_f32_e32 v1, v1, v28
	v_mul_f32_e32 v23, v23, v28
	v_mul_f32_e32 v2, v2, v28
	v_mul_f32_e32 v20, v20, v28
	v_mul_f32_e32 v21, v21, v28
	v_mul_f32_e32 v24, v24, v28
	v_mul_f32_e32 v3, v3, v28
	v_or_b32_e32 v27, v66, v38
	v_mad_u64_u32 v[56:57], s[0:1], v27, s27, v[30:31]
	v_add_u32_e32 v58, s29, v27
	s_add_u32 s0, s13, s14
	s_addc_u32 s1, s18, 0
	v_mov_b32_e32 v33, v25
	v_lshlrev_b32_e32 v32, 3, v39
	v_ashrrev_i32_e32 v59, 31, v58
	v_or_b32_e32 v38, s29, v38
	s_waitcnt vmcnt(2)
	v_accvgpr_read_b32 v4, a100
	v_accvgpr_read_b32 v5, a101
	v_accvgpr_read_b32 v6, a102
	v_accvgpr_read_b32 v7, a103
	v_accvgpr_read_b32 v16, a104
	v_accvgpr_read_b32 v17, a105
	v_accvgpr_read_b32 v18, a106
	v_accvgpr_read_b32 v19, a107
	v_fma_f32 v0, v17, v0, v5
	v_fmac_f32_e32 v7, v19, v1
	s_waitcnt vmcnt(0)
	v_accvgpr_read_b32 v12, a108
	v_accvgpr_read_b32 v13, a109
	v_accvgpr_read_b32 v14, a110
	v_accvgpr_read_b32 v15, a111
	v_accvgpr_read_b32 v8, a112
	v_accvgpr_read_b32 v9, a113
	v_accvgpr_read_b32 v10, a114
	v_accvgpr_read_b32 v11, a115
	s_mov_b64 s[64:65], 0
	v_fma_f32 v1, v12, v23, v8
	v_fma_f32 v2, v13, v2, v9
	v_fma_f32 v4, v16, v20, v4
	v_fma_f32 v5, v18, v21, v6
	v_fma_f32 v6, v14, v24, v10
	v_fmac_f32_e32 v11, v15, v3
	v_cvt_pk_bf16_f32 v0, v4, v0
	v_cvt_pk_bf16_f32 v3, v5, v7
	v_cvt_pk_bf16_f32 v1, v1, v2
	v_cvt_pk_bf16_f32 v2, v6, v11
	ds_write_b16 v22, v0 offset:34816
	ds_write_b16_d16_hi v22, v0 offset:35088
	ds_write_b16 v22, v3 offset:35360
	ds_write_b16_d16_hi v22, v3 offset:35632
	ds_write_b16 v22, v1 offset:35904
	ds_write_b16_d16_hi v22, v1 offset:36176
	ds_write_b16 v22, v2 offset:36448
	ds_write_b16_d16_hi v22, v2 offset:36720
	s_waitcnt lgkmcnt(0)
	s_barrier
	ds_read_b128 v[0:3], v64 offset:34816
	ds_read_b128 v[4:7], v56
	ds_read_b128 v[8:11], v56 offset:64
	ds_read_b128 v[12:15], v64 offset:34880
	ds_read_b128 v[16:19], v64 offset:39168
	ds_read_b128 v[20:23], v64 offset:39232
	ds_read_b128 v[28:31], v64 offset:43520
	ds_read_b128 v[34:37], v64 offset:43584
	ds_read_b128 v[40:43], v64 offset:47872
	ds_read_b128 v[44:47], v64 offset:47936
	s_waitcnt lgkmcnt(8)
	v_mfma_f32_16x16x32_bf16 a[0:3], v[0:3], v[4:7], 0
	s_waitcnt lgkmcnt(5)
	v_mfma_f32_16x16x32_bf16 a[4:7], v[16:19], v[4:7], 0
	s_waitcnt lgkmcnt(3)
	v_mfma_f32_16x16x32_bf16 a[8:11], v[28:31], v[4:7], 0
	s_waitcnt lgkmcnt(1)
	v_mfma_f32_16x16x32_bf16 a[12:15], v[40:43], v[4:7], 0
	ds_read_b128 v[4:7], v56 offset:4352
	ds_read_b128 v[48:51], v56 offset:4416
	s_waitcnt lgkmcnt(1)
	v_mfma_f32_16x16x32_bf16 a[16:19], v[0:3], v[4:7], 0
	v_and_b32_e32 v0, 64, v26
	v_lshlrev_b32_e32 v24, 1, v0
	v_add_u32_e32 v0, s30, v27
	v_mfma_f32_16x16x32_bf16 a[20:23], v[16:19], v[4:7], 0
	v_ashrrev_i32_e32 v1, 31, v0
	v_lshl_add_u64 v[60:61], v[0:1], 2, s[72:73]
	v_mfma_f32_16x16x32_bf16 a[24:27], v[28:31], v[4:7], 0
	ds_read_b128 v[26:29], v64 offset:34944
	v_lshlrev_b64 v[30:31], 11, v[58:59]
	v_mfma_f32_16x16x32_bf16 a[28:31], v[40:43], v[4:7], 0
	v_mfma_f32_16x16x32_bf16 a[4:7], v[20:23], v[8:11], a[4:7]
	s_waitcnt lgkmcnt(1)
	v_mfma_f32_16x16x32_bf16 a[20:23], v[20:23], v[48:51], a[20:23]
	ds_read_b128 v[20:23], v56 offset:128
	ds_read_b128 v[40:43], v64 offset:39296
	v_mfma_f32_16x16x32_bf16 a[0:3], v[12:15], v[8:11], a[0:3]
	v_mfma_f32_16x16x32_bf16 a[8:11], v[34:37], v[8:11], a[8:11]
	v_mfma_f32_16x16x32_bf16 a[12:15], v[44:47], v[8:11], a[12:15]
	v_mfma_f32_16x16x32_bf16 a[16:19], v[12:15], v[48:51], a[16:19]
	v_lshl_add_u64 v[12:13], s[0:1], 0, v[24:25]
	v_lshl_add_u64 v[62:63], v[12:13], 0, v[32:33]
	s_add_u32 s0, s19, s14
	v_mfma_f32_16x16x32_bf16 a[32:35], v[34:37], v[48:51], a[24:27]
	s_addc_u32 s1, s20, 0
	s_add_i32 s28, s28, s3
	s_add_i32 s21, s21, s22
	v_mfma_f32_16x16x32_bf16 a[28:31], v[44:47], v[48:51], a[28:31]
	ds_read_b128 v[44:47], v64 offset:43648
	ds_read_b128 v[16:19], v56 offset:192
	ds_read_b128 v[0:3], v64 offset:35008
	ds_read_b128 v[48:51], v64 offset:48000
	ds_read_b128 v[4:7], v64 offset:39360
	ds_read_b128 v[8:11], v64 offset:43712
	ds_read_b128 v[52:55], v56 offset:4480
	ds_read_b128 v[12:15], v64 offset:48064
	v_lshl_add_u64 v[64:65], v[62:63], 0, v[30:31]
	s_waitcnt lgkmcnt(9)
	v_mfma_f32_16x16x32_bf16 a[36:39], v[26:29], v[20:23], a[0:3]
	global_load_dwordx2 v[36:37], v[64:65], off
	global_load_dwordx2 v[34:35], v[64:65], off offset:32
	global_load_dwordx2 v[30:31], v[64:65], off offset:64
	s_waitcnt lgkmcnt(8)
	v_mfma_f32_16x16x32_bf16 a[40:43], v[40:43], v[20:23], a[4:7]
	global_load_dword v39, v[60:61], off offset:64
	s_add_i32 s23, s23, s24
	s_cmpk_lt_i32 s28, 0x400
	s_waitcnt lgkmcnt(7)
	v_mfma_f32_16x16x32_bf16 a[44:47], v[44:47], v[20:23], a[8:11]
	s_waitcnt lgkmcnt(4)
	v_mfma_f32_16x16x32_bf16 a[48:51], v[48:51], v[20:23], a[12:15]
	ds_read_b128 v[20:23], v56 offset:4544
	global_load_dword v56, v[60:61], off
	s_waitcnt lgkmcnt(2)
	v_mfma_f32_16x16x32_bf16 a[24:27], v[26:29], v[52:55], a[16:19]
	v_add_u32_e32 v26, 16, v58
	global_load_dwordx2 v[28:29], v[64:65], off offset:96
	v_ashrrev_i32_e32 v27, 31, v26
	v_lshlrev_b64 v[26:27], 11, v[26:27]
	v_mfma_f32_16x16x32_bf16 a[16:19], v[40:43], v[52:55], a[20:23]
	v_lshl_add_u64 v[40:41], v[62:63], 0, v[26:27]
	global_load_dwordx2 v[26:27], v[40:41], off
	v_add_u32_e32 v42, v38, v66
	v_mfma_f32_16x16x32_bf16 a[4:7], v[44:47], v[52:55], a[32:35]
	v_or_b32_e32 v44, 16, v42
	v_ashrrev_i32_e32 v43, 31, v42
	v_ashrrev_i32_e32 v45, 31, v44
	v_mfma_f32_16x16x32_bf16 a[8:11], v[0:3], v[16:19], a[36:39]
	s_waitcnt vmcnt(4)
	v_lshlrev_b32_e32 v46, 16, v31
	v_mfma_f32_16x16x32_bf16 a[12:15], v[4:7], v[16:19], a[40:43]
	v_and_b32_e32 v31, 0xffff0000, v31
	s_waitcnt vmcnt(1)
	v_lshlrev_b32_e32 v47, 16, v28
	v_mfma_f32_16x16x32_bf16 a[20:23], v[8:11], v[16:19], a[44:47]
	v_and_b32_e32 v28, 0xffff0000, v28
	s_waitcnt lgkmcnt(0)
	v_mfma_f32_16x16x32_bf16 a[24:27], v[0:3], v[20:23], a[24:27]
	v_lshl_add_u64 v[0:1], s[0:1], 0, v[24:25]
	v_lshl_add_u64 v[0:1], v[0:1], 0, v[32:33]
	v_mfma_f32_16x16x32_bf16 a[16:19], v[4:7], v[20:23], a[16:19]
	v_mfma_f32_16x16x32_bf16 a[4:7], v[8:11], v[20:23], a[4:7]
	global_load_dwordx2 v[8:9], v[40:41], off offset:32
	global_load_dwordx2 v[4:5], v[40:41], off offset:64
	global_load_dwordx2 v[2:3], v[40:41], off offset:96
	v_accvgpr_read_b32 v10, a8
	v_accvgpr_read_b32 v11, a9
	v_mfma_f32_16x16x32_bf16 a[0:3], v[48:51], v[52:55], a[28:31]
	v_lshlrev_b32_e32 v41, 16, v36
	v_add_f32_e32 v10, v56, v10
	v_and_b32_e32 v36, 0xffff0000, v36
	v_mfma_f32_16x16x32_bf16 a[28:31], v[12:15], v[16:19], a[48:51]
	v_lshlrev_b64 v[16:17], 11, v[42:43]
	v_lshlrev_b64 v[18:19], 11, v[44:45]
	v_add_f32_e32 v11, v56, v11
	v_mfma_f32_16x16x32_bf16 a[0:3], v[12:15], v[20:23], a[0:3]
	v_accvgpr_read_b32 v12, a10
	v_accvgpr_read_b32 v13, a11
	v_accvgpr_read_b32 v14, a12
	v_accvgpr_read_b32 v15, a13
	v_mul_f32_e32 v10, v10, v41
	v_lshl_add_u64 v[6:7], v[0:1], 0, v[16:17]
	v_lshl_add_u64 v[0:1], v[0:1], 0, v[18:19]
	v_accvgpr_read_b32 v16, a14
	v_accvgpr_read_b32 v17, a15
	v_accvgpr_read_b32 v18, a20
	v_accvgpr_read_b32 v19, a21
	v_lshlrev_b32_e32 v42, 16, v37
	v_add_f32_e32 v12, v56, v12
	v_and_b32_e32 v37, 0xffff0000, v37
	v_add_f32_e32 v13, v56, v13
	v_lshlrev_b32_e32 v43, 16, v34
	v_add_f32_e32 v14, v56, v14
	v_and_b32_e32 v34, 0xffff0000, v34
	v_add_f32_e32 v15, v56, v15
	v_mul_f32_e32 v11, v11, v36
	v_cvt_pk_bf16_f32 v10, v10, v11
	v_accvgpr_read_b32 v20, a22
	v_accvgpr_read_b32 v21, a23
	v_accvgpr_read_b32 v22, a28
	v_accvgpr_read_b32 v23, a29
	v_lshlrev_b32_e32 v44, 16, v35
	v_add_f32_e32 v16, v56, v16
	v_and_b32_e32 v35, 0xffff0000, v35
	v_add_f32_e32 v17, v56, v17
	v_lshlrev_b32_e32 v45, 16, v30
	v_add_f32_e32 v18, v56, v18
	v_and_b32_e32 v30, 0xffff0000, v30
	v_add_f32_e32 v19, v56, v19
	v_mul_f32_e32 v12, v12, v42
	v_mul_f32_e32 v13, v13, v37
	v_mul_f32_e32 v14, v14, v43
	v_mul_f32_e32 v15, v15, v34
	v_cvt_pk_bf16_f32 v11, v12, v13
	global_store_dwordx2 v[6:7], v[10:11], off
	v_cvt_pk_bf16_f32 v10, v14, v15
	v_accvgpr_read_b32 v24, a30
	v_accvgpr_read_b32 v32, a31
	v_add_f32_e32 v20, v56, v20
	v_add_f32_e32 v21, v56, v21
	v_add_f32_e32 v22, v56, v22
	v_add_f32_e32 v23, v56, v23
	v_mul_f32_e32 v16, v16, v44
	v_mul_f32_e32 v17, v17, v35
	v_mul_f32_e32 v18, v18, v45
	v_mul_f32_e32 v19, v19, v30
	v_cvt_pk_bf16_f32 v11, v16, v17
	global_store_dwordx2 v[6:7], v[10:11], off offset:32
	v_cvt_pk_bf16_f32 v10, v18, v19
	v_lshlrev_b32_e32 v48, 16, v29
	v_add_f32_e32 v24, v56, v24
	v_and_b32_e32 v29, 0xffff0000, v29
	v_add_f32_e32 v32, v56, v32
	v_mul_f32_e32 v20, v20, v46
	v_mul_f32_e32 v21, v21, v31
	v_mul_f32_e32 v22, v22, v47
	v_mul_f32_e32 v23, v23, v28
	v_cvt_pk_bf16_f32 v11, v20, v21
	global_store_dwordx2 v[6:7], v[10:11], off offset:64
	v_cvt_pk_bf16_f32 v10, v22, v23
	v_mul_f32_e32 v24, v24, v48
	v_mul_f32_e32 v28, v32, v29
	v_cvt_pk_bf16_f32 v11, v24, v28
	global_store_dwordx2 v[6:7], v[10:11], off offset:96
	v_accvgpr_read_b32 v10, a27
	v_accvgpr_read_b32 v33, a24
	v_accvgpr_read_b32 v38, a25
	v_accvgpr_read_b32 v40, a26
	s_waitcnt vmcnt(7)
	v_and_b32_e32 v7, 0xffff0000, v27
	v_add_f32_e32 v10, v39, v10
	v_lshlrev_b32_e32 v49, 16, v26
	v_add_f32_e32 v33, v39, v33
	v_and_b32_e32 v26, 0xffff0000, v26
	v_add_f32_e32 v38, v39, v38
	v_lshlrev_b32_e32 v50, 16, v27
	v_add_f32_e32 v40, v39, v40
	v_mul_f32_e32 v7, v10, v7
	v_mul_f32_e32 v29, v33, v49
	v_mul_f32_e32 v26, v38, v26
	v_mul_f32_e32 v30, v40, v50
	v_cvt_pk_bf16_f32 v6, v29, v26
	v_cvt_pk_bf16_f32 v7, v30, v7
	global_store_dwordx2 v[0:1], v[6:7], off
	v_accvgpr_read_b32 v7, a16
	s_waitcnt vmcnt(7)
	v_lshlrev_b32_e32 v6, 16, v8
	v_add_f32_e32 v7, v39, v7
	v_mul_f32_e32 v6, v7, v6
	v_and_b32_e32 v7, 0xffff0000, v8
	v_accvgpr_read_b32 v8, a17
	v_add_f32_e32 v8, v39, v8
	v_mul_f32_e32 v7, v8, v7
	v_accvgpr_read_b32 v8, a18
	v_cvt_pk_bf16_f32 v6, v6, v7
	v_lshlrev_b32_e32 v7, 16, v9
	v_add_f32_e32 v8, v39, v8
	v_mul_f32_e32 v7, v8, v7
	v_and_b32_e32 v8, 0xffff0000, v9
	v_accvgpr_read_b32 v9, a19
	v_add_f32_e32 v9, v39, v9
	v_mul_f32_e32 v8, v9, v8
	v_cvt_pk_bf16_f32 v7, v7, v8
	global_store_dwordx2 v[0:1], v[6:7], off offset:32
	v_accvgpr_read_b32 v7, a4
	s_waitcnt vmcnt(7)
	v_lshlrev_b32_e32 v6, 16, v4
	v_add_f32_e32 v7, v39, v7
	v_mul_f32_e32 v6, v7, v6
	v_accvgpr_read_b32 v7, a5
	v_and_b32_e32 v4, 0xffff0000, v4
	v_add_f32_e32 v7, v39, v7
	v_mul_f32_e32 v4, v7, v4
	v_accvgpr_read_b32 v7, a6
	v_cvt_pk_bf16_f32 v4, v6, v4
	v_lshlrev_b32_e32 v6, 16, v5
	v_add_f32_e32 v7, v39, v7
	v_mul_f32_e32 v6, v7, v6
	v_accvgpr_read_b32 v7, a7
	v_and_b32_e32 v5, 0xffff0000, v5
	v_add_f32_e32 v7, v39, v7
	v_mul_f32_e32 v5, v7, v5
	v_cvt_pk_bf16_f32 v5, v6, v5
	global_store_dwordx2 v[0:1], v[4:5], off offset:64
	v_accvgpr_read_b32 v5, a0
	s_waitcnt vmcnt(7)
	v_lshlrev_b32_e32 v4, 16, v2
	v_add_f32_e32 v5, v39, v5
	v_mul_f32_e32 v4, v5, v4
	v_accvgpr_read_b32 v5, a1
	v_and_b32_e32 v2, 0xffff0000, v2
	v_add_f32_e32 v5, v39, v5
	v_mul_f32_e32 v2, v5, v2
	v_accvgpr_read_b32 v5, a2
	v_cvt_pk_bf16_f32 v2, v4, v2
	v_lshlrev_b32_e32 v4, 16, v3
	v_add_f32_e32 v5, v39, v5
	v_mul_f32_e32 v4, v5, v4
	v_accvgpr_read_b32 v5, a3
	v_and_b32_e32 v3, 0xffff0000, v3
	v_add_f32_e32 v5, v39, v5
	v_mul_f32_e32 v3, v5, v3
	v_cvt_pk_bf16_f32 v3, v4, v3
	global_store_dwordx2 v[0:1], v[2:3], off offset:96
	s_barrier
	s_cbranch_scc0 .LBB0_1212
